# MLA K-fragment address registers biased once per unit so every buffer/half is an immediate offset (16 fewer v_add per odd tile)
# speedup vs baseline: 1.0051x; 1.0051x over previous
.LBB0_561:
	s_waitcnt lgkmcnt(0)
	s_barrier
	v_add_u32_e32 v193, 0x8000, v193
	v_add_u32_e32 v186, 0x8000, v186
	v_add_u32_e32 v187, 0x8000, v187
	v_add_u32_e32 v188, 0x8000, v188
	v_add_u32_e32 v189, 0x8000, v189
	v_add_u32_e32 v190, 0x8000, v190
	v_add_u32_e32 v191, 0x8000, v191
	v_add_u32_e32 v192, 0x8000, v192
	v_add_u32_e32 v203, 0xc000, v203
	v_add_u32_e32 v204, 0xc000, v204
	v_add_u32_e32 v205, 0xc000, v205
	v_add_u32_e32 v206, 0xc000, v206
	s_cmp_lt_u32 s3, 4
	s_cbranch_scc1 .Lmla_prio_done
	s_setprio 1

.Lmla_loop:
	ds_read_b128 v[230:233], v193 offset:24576
	ds_read_b128 v[234:237], v186 offset:24576
	ds_read_b128 v[238:241], v187 offset:24576
	ds_read_b128 v[242:245], v188 offset:24576
	s_cmp_lt_u32 s58, s18
	s_cselect_b32 s0, 0, s18
	s_cselect_b32 s1, s6, s13
	s_lshl_b32 s0, s0, 6
	s_sub_i32 s0, s1, s0
	s_add_i32 s0, s51, s0
	s_ashr_i32 s1, s0, 31
	s_lshl_b64 s[10:11], s[0:1], 12
	s_add_u32 s16, s20, s10
	s_addc_u32 s17, s21, s11
	v_exp_f32_e32 v64, v64
	v_exp_f32_e32 v65, v65
	v_add_f32_e32 v212, v64, v212
	v_exp_f32_e32 v66, v66
	v_add_f32_e32 v212, v65, v212
	v_exp_f32_e32 v67, v67
	s_waitcnt lgkmcnt(3)
	v_mfma_f32_32x32x16_bf16 v[80:95], v[230:233], v[124:127], 0
	ds_read_b128 v[230:233], v189 offset:24576
	s_cmp_eq_u32 s58, 2
	s_cbranch_scc1 .Lmla_skipv0_o
	s_mov_b32 m0, s54
	v_lshl_add_u64 v[254:255], v[164:165], 1, s[100:101]
	global_load_lds_dwordx4 v[254:255], off
.Lmla_skipv0_o:
	v_add_f32_e32 v212, v66, v212
	v_exp_f32_e32 v68, v68
	v_add_f32_e32 v212, v67, v212
	v_exp_f32_e32 v69, v69
	s_waitcnt lgkmcnt(3)
	v_mfma_f32_32x32x16_bf16 v[80:95], v[234:237], v[120:123], v[80:95]
	ds_read_b128 v[234:237], v190 offset:24576
	s_cmp_eq_u32 s58, 2
	s_cbranch_scc1 .Lmla_skipv1_o
	s_mov_b32 m0, s55
	v_lshl_add_u64 v[254:255], v[166:167], 1, s[100:101]
	global_load_lds_dwordx4 v[254:255], off
.Lmla_skipv1_o:
	v_add_f32_e32 v212, v68, v212
	v_exp_f32_e32 v70, v70
	v_add_f32_e32 v212, v69, v212
	v_exp_f32_e32 v71, v71
	s_waitcnt lgkmcnt(3)
	v_mfma_f32_32x32x16_bf16 v[80:95], v[238:241], v[116:119], v[80:95]
	ds_read_b128 v[238:241], v191 offset:24576
	v_add_f32_e32 v212, v70, v212
	v_exp_f32_e32 v72, v72
	v_add_f32_e32 v212, v71, v212
	v_exp_f32_e32 v73, v73
	s_waitcnt lgkmcnt(3)
	v_mfma_f32_32x32x16_bf16 v[80:95], v[242:245], v[112:115], v[80:95]
	ds_read_b128 v[242:245], v192 offset:24576
	s_mov_b32 m0, s23
	v_lshl_add_u64 v[254:255], v[160:161], 1, s[16:17]
	global_load_lds_dwordx4 v[254:255], off
	v_add_f32_e32 v212, v72, v212
	v_exp_f32_e32 v74, v74
	v_add_f32_e32 v212, v73, v212
	v_exp_f32_e32 v75, v75
	s_waitcnt lgkmcnt(3)
	v_mfma_f32_32x32x16_bf16 v[80:95], v[230:233], v[108:111], v[80:95]
	ds_read_b128 v[230:233], v203 offset:24576
	v_add_f32_e32 v212, v74, v212
	v_exp_f32_e32 v76, v76
	v_add_f32_e32 v212, v75, v212
	v_exp_f32_e32 v77, v77
	s_waitcnt lgkmcnt(3)
	v_mfma_f32_32x32x16_bf16 v[80:95], v[234:237], v[104:107], v[80:95]
	ds_read_b128 v[234:237], v204 offset:24576
	s_mov_b32 m0, s7
	v_lshl_add_u64 v[254:255], v[162:163], 1, s[16:17]
	global_load_lds_dwordx4 v[254:255], off
	v_add_f32_e32 v212, v76, v212
	v_exp_f32_e32 v78, v78
	v_add_f32_e32 v212, v77, v212
	v_exp_f32_e32 v79, v79
	s_waitcnt lgkmcnt(3)
	v_mfma_f32_32x32x16_bf16 v[80:95], v[238:241], v[100:103], v[80:95]
	ds_read_b128 v[238:241], v205 offset:24576
	v_add_f32_e32 v212, v78, v212
	v_add_f32_e32 v212, v79, v212
	v_mov_b32_e32 v213, v212
	s_waitcnt lgkmcnt(3)
	v_mfma_f32_32x32x16_bf16 v[80:95], v[242:245], v[96:99], v[80:95]
	ds_read_b128 v[242:245], v206 offset:24576
	s_mov_b32 m0, s30
	v_mad_i64_i32 v[254:255], s[0:1], s0, v180, v[168:169]
	global_load_lds_dwordx4 v[254:255], off
	s_add_u32 s100, s16, 0x100
	s_addc_u32 s101, s17, 0
	v_cvt_pk_bf16_f32 v152, v64, v65
	v_cvt_pk_bf16_f32 v153, v66, v67
	v_cvt_pk_bf16_f32 v154, v68, v69
	s_waitcnt lgkmcnt(3)
	v_mfma_f32_32x32x16_bf16 v[80:95], v[230:233], v[128:131], v[80:95]
	ds_read_b128 v[230:233], v193 offset:32768
	v_cvt_pk_bf16_f32 v155, v70, v71
	v_cvt_pk_bf16_f32 v156, v72, v73
	v_cvt_pk_bf16_f32 v157, v74, v75
	s_waitcnt lgkmcnt(3)
	v_mfma_f32_32x32x16_bf16 v[80:95], v[234:237], v[132:135], v[80:95]
	ds_read_b128 v[234:237], v186 offset:32768
	v_cvt_pk_bf16_f32 v158, v76, v77
	v_cvt_pk_bf16_f32 v159, v78, v79
	v_permlane32_swap_b32_e32 v212, v213
	s_waitcnt lgkmcnt(3)
	v_mfma_f32_32x32x16_bf16 v[80:95], v[238:241], v[136:139], v[80:95]
	ds_read_b128 v[238:241], v187 offset:32768
	v_add_f32_e32 v252, v212, v213
	v_fma_f32 v183, v207, v183, v252
	v_permlane32_swap_b32_e32 v152, v154
	s_waitcnt lgkmcnt(3)
	v_mfma_f32_32x32x16_bf16 v[80:95], v[242:245], v[140:143], v[80:95]
	ds_read_b128 v[242:245], v188 offset:32768
	v_permlane32_swap_b32_e32 v153, v155
	v_permlane32_swap_b32_e32 v156, v158
	v_permlane32_swap_b32_e32 v157, v159
	s_waitcnt lgkmcnt(3)
	v_mfma_f32_32x32x16_bf16 v[64:79], v[230:233], v[124:127], 0
	ds_read_b128 v[230:233], v189 offset:32768
	s_waitcnt lgkmcnt(3)
	v_mfma_f32_32x32x16_bf16 v[64:79], v[234:237], v[120:123], v[64:79]
	ds_read_b128 v[234:237], v190 offset:32768
	s_waitcnt lgkmcnt(3)
	v_mfma_f32_32x32x16_bf16 v[64:79], v[238:241], v[116:119], v[64:79]
	ds_read_b128 v[238:241], v191 offset:32768
	s_waitcnt lgkmcnt(3)
	v_mfma_f32_32x32x16_bf16 v[64:79], v[242:245], v[112:115], v[64:79]
	ds_read_b128 v[242:245], v192 offset:32768
	s_waitcnt lgkmcnt(3)
	v_mfma_f32_32x32x16_bf16 v[64:79], v[230:233], v[108:111], v[64:79]
	ds_read_b128 v[230:233], v203 offset:28672
	s_waitcnt lgkmcnt(3)
	v_mfma_f32_32x32x16_bf16 v[64:79], v[234:237], v[104:107], v[64:79]
	ds_read_b128 v[234:237], v204 offset:28672
	s_waitcnt lgkmcnt(3)
	v_mfma_f32_32x32x16_bf16 v[64:79], v[238:241], v[100:103], v[64:79]
	ds_read_b128 v[238:241], v205 offset:28672
	v_max_f32_e32 v249, v80, v81
	v_max3_f32 v249, v249, v82, v83
	s_waitcnt lgkmcnt(3)
	v_mfma_f32_32x32x16_bf16 v[64:79], v[242:245], v[96:99], v[64:79]
	ds_read_b128 v[242:245], v206 offset:28672
	v_max3_f32 v249, v249, v84, v85
	v_max3_f32 v249, v249, v86, v87
	s_waitcnt lgkmcnt(3)
	v_mfma_f32_32x32x16_bf16 v[64:79], v[230:233], v[128:131], v[64:79]
	ds_read_b64_tr_b16 v[214:215], v185
	ds_read_b64_tr_b16 v[216:217], v185 offset:2048
	v_max3_f32 v249, v249, v88, v89
	v_max3_f32 v249, v249, v90, v91
	s_waitcnt lgkmcnt(4)
	v_mfma_f32_32x32x16_bf16 v[64:79], v[234:237], v[132:135], v[64:79]
	ds_read_b64_tr_b16 v[218:219], v185 offset:4096
	ds_read_b64_tr_b16 v[220:221], v185 offset:6144
	v_max3_f32 v249, v249, v92, v93
	v_max3_f32 v249, v249, v94, v95
	s_waitcnt lgkmcnt(5)
	v_mfma_f32_32x32x16_bf16 v[64:79], v[238:241], v[136:139], v[64:79]
	ds_read_b64_tr_b16 v[222:223], v185 offset:8192
	ds_read_b64_tr_b16 v[224:225], v185 offset:10240
	s_waitcnt lgkmcnt(6)
	v_mfma_f32_32x32x16_bf16 v[64:79], v[242:245], v[140:143], v[64:79]
	ds_read_b64_tr_b16 v[226:227], v185 offset:12288
	ds_read_b64_tr_b16 v[228:229], v185 offset:14336
	s_waitcnt lgkmcnt(6)
	v_mfma_f32_32x32x16_bf16 v[0:15], v[214:217], v[144:147], v[0:15]
	ds_read_b64_tr_b16 v[214:215], v185 offset:512
	ds_read_b64_tr_b16 v[216:217], v185 offset:2560
	s_waitcnt lgkmcnt(6)
	v_mfma_f32_32x32x16_bf16 v[0:15], v[218:221], v[148:151], v[0:15]
	ds_read_b64_tr_b16 v[218:219], v185 offset:4608
	ds_read_b64_tr_b16 v[220:221], v185 offset:6656
	s_waitcnt lgkmcnt(6)
	v_mfma_f32_32x32x16_bf16 v[0:15], v[222:225], v[152:155], v[0:15]
	ds_read_b64_tr_b16 v[222:223], v185 offset:8704
	ds_read_b64_tr_b16 v[224:225], v185 offset:10752
	s_waitcnt lgkmcnt(6)
	v_mfma_f32_32x32x16_bf16 v[0:15], v[226:229], v[156:159], v[0:15]
	ds_read_b64_tr_b16 v[226:227], v185 offset:12800
	ds_read_b64_tr_b16 v[228:229], v185 offset:14848
	s_waitcnt lgkmcnt(6)
	v_mfma_f32_32x32x16_bf16 v[48:63], v[214:217], v[144:147], v[48:63]
	ds_read_b64_tr_b16 v[214:215], v185 offset:1024
	ds_read_b64_tr_b16 v[216:217], v185 offset:3072
	v_max3_f32 v249, v249, v64, v65
	v_max3_f32 v249, v249, v66, v67
	v_max3_f32 v249, v249, v68, v69
	v_max3_f32 v249, v249, v70, v71
	v_max3_f32 v249, v249, v72, v73
	v_max3_f32 v249, v249, v74, v75
	v_max3_f32 v249, v249, v76, v77
	v_max3_f32 v249, v249, v78, v79
	s_waitcnt lgkmcnt(6)
	v_mfma_f32_32x32x16_bf16 v[48:63], v[218:221], v[148:151], v[48:63]
	ds_read_b64_tr_b16 v[218:219], v185 offset:5120
	ds_read_b64_tr_b16 v[220:221], v185 offset:7168
	v_mov_b32_e32 v250, v249
	s_nop 1
	v_permlane32_swap_b32_e32 v249, v250
	v_max_f32_e32 v249, v249, v250
	v_sub_f32_e32 v250, v249, v208
	v_cmp_ge_f32_e32 vcc, s40, v250
	v_max_f32_e32 v249, v208, v249
	v_sub_f32_e32 v250, v208, v249
	s_waitcnt lgkmcnt(6)
	v_mfma_f32_32x32x16_bf16 v[48:63], v[222:225], v[152:155], v[48:63]
	ds_read_b64_tr_b16 v[222:223], v185 offset:9216
	ds_read_b64_tr_b16 v[224:225], v185 offset:11264
	v_mul_f32_e32 v250, 0x3dd53b94, v250
	v_exp_f32_e32 v250, v250
	s_cmp_eq_u64 vcc, exec
	s_cselect_b64 s[10:11], -1, 0
	v_cndmask_b32_e64 v207, v250, 1.0, s[10:11]
	v_cndmask_b32_e64 v208, v249, v208, s[10:11]
	v_mul_f32_e32 v251, 0xbdd53b94, v208
	v_fmamk_f32 v80, v80, 0x3dd53b94, v251
	s_waitcnt lgkmcnt(6)
	v_mfma_f32_32x32x16_bf16 v[48:63], v[226:229], v[156:159], v[48:63]
	ds_read_b64_tr_b16 v[226:227], v185 offset:13312
	ds_read_b64_tr_b16 v[228:229], v185 offset:15360
	v_fmamk_f32 v81, v81, 0x3dd53b94, v251
	v_fmamk_f32 v82, v82, 0x3dd53b94, v251
	v_fmamk_f32 v83, v83, 0x3dd53b94, v251
	v_fmamk_f32 v84, v84, 0x3dd53b94, v251
	v_fmamk_f32 v85, v85, 0x3dd53b94, v251
	v_fmamk_f32 v86, v86, 0x3dd53b94, v251
	v_fmamk_f32 v87, v87, 0x3dd53b94, v251
	s_waitcnt lgkmcnt(6)
	v_mfma_f32_32x32x16_bf16 v[32:47], v[214:217], v[144:147], v[32:47]
	ds_read_b64_tr_b16 v[214:215], v185 offset:1536
	ds_read_b64_tr_b16 v[216:217], v185 offset:3584
	v_fmamk_f32 v88, v88, 0x3dd53b94, v251
	v_fmamk_f32 v89, v89, 0x3dd53b94, v251
	v_fmamk_f32 v90, v90, 0x3dd53b94, v251
	v_fmamk_f32 v91, v91, 0x3dd53b94, v251
	v_fmamk_f32 v92, v92, 0x3dd53b94, v251
	v_fmamk_f32 v93, v93, 0x3dd53b94, v251
	v_fmamk_f32 v94, v94, 0x3dd53b94, v251
	s_waitcnt lgkmcnt(6)
	v_mfma_f32_32x32x16_bf16 v[32:47], v[218:221], v[148:151], v[32:47]
	ds_read_b64_tr_b16 v[218:219], v185 offset:5632
	ds_read_b64_tr_b16 v[220:221], v185 offset:7680
	v_fmamk_f32 v95, v95, 0x3dd53b94, v251
	v_exp_f32_e32 v80, v80
	v_fmamk_f32 v64, v64, 0x3dd53b94, v251
	v_exp_f32_e32 v81, v81
	v_fmamk_f32 v65, v65, 0x3dd53b94, v251
	v_add_f32_e32 v212, 0, v80
	v_exp_f32_e32 v82, v82
	s_waitcnt lgkmcnt(6)
	v_mfma_f32_32x32x16_bf16 v[32:47], v[222:225], v[152:155], v[32:47]
	ds_read_b64_tr_b16 v[222:223], v185 offset:9728
	ds_read_b64_tr_b16 v[224:225], v185 offset:11776
	v_fmamk_f32 v66, v66, 0x3dd53b94, v251
	v_add_f32_e32 v212, v81, v212
	v_exp_f32_e32 v83, v83
	v_fmamk_f32 v67, v67, 0x3dd53b94, v251
	v_add_f32_e32 v212, v82, v212
	v_exp_f32_e32 v84, v84
	v_fmamk_f32 v68, v68, 0x3dd53b94, v251
	s_waitcnt lgkmcnt(6)
	v_mfma_f32_32x32x16_bf16 v[32:47], v[226:229], v[156:159], v[32:47]
	ds_read_b64_tr_b16 v[226:227], v185 offset:13824
	ds_read_b64_tr_b16 v[228:229], v185 offset:15872
	v_add_f32_e32 v212, v83, v212
	v_exp_f32_e32 v85, v85
	v_fmamk_f32 v69, v69, 0x3dd53b94, v251
	v_add_f32_e32 v212, v84, v212
	v_exp_f32_e32 v86, v86
	v_fmamk_f32 v70, v70, 0x3dd53b94, v251
	v_add_f32_e32 v212, v85, v212
	s_waitcnt lgkmcnt(6)
	v_mfma_f32_32x32x16_bf16 v[16:31], v[214:217], v[144:147], v[16:31]
	v_exp_f32_e32 v87, v87
	v_fmamk_f32 v71, v71, 0x3dd53b94, v251
	v_add_f32_e32 v212, v86, v212
	v_exp_f32_e32 v88, v88
	v_fmamk_f32 v72, v72, 0x3dd53b94, v251
	v_add_f32_e32 v212, v87, v212
	v_exp_f32_e32 v89, v89
	s_waitcnt lgkmcnt(4)
	v_mfma_f32_32x32x16_bf16 v[16:31], v[218:221], v[148:151], v[16:31]
	v_fmamk_f32 v73, v73, 0x3dd53b94, v251
	v_add_f32_e32 v212, v88, v212
	v_exp_f32_e32 v90, v90
	v_fmamk_f32 v74, v74, 0x3dd53b94, v251
	v_add_f32_e32 v212, v89, v212
	v_exp_f32_e32 v91, v91
	v_fmamk_f32 v75, v75, 0x3dd53b94, v251
	s_waitcnt lgkmcnt(2)
	v_mfma_f32_32x32x16_bf16 v[16:31], v[222:225], v[152:155], v[16:31]
	v_add_f32_e32 v212, v90, v212
	v_exp_f32_e32 v92, v92
	v_fmamk_f32 v76, v76, 0x3dd53b94, v251
	v_add_f32_e32 v212, v91, v212
	v_exp_f32_e32 v93, v93
	v_fmamk_f32 v77, v77, 0x3dd53b94, v251
	v_add_f32_e32 v212, v92, v212
	s_waitcnt lgkmcnt(0)
	v_mfma_f32_32x32x16_bf16 v[16:31], v[226:229], v[156:159], v[16:31]
	v_exp_f32_e32 v94, v94
	v_fmamk_f32 v78, v78, 0x3dd53b94, v251
	v_add_f32_e32 v212, v93, v212
	v_exp_f32_e32 v95, v95
	v_fmamk_f32 v79, v79, 0x3dd53b94, v251
	v_add_f32_e32 v212, v94, v212
	v_add_f32_e32 v212, v95, v212
	v_cvt_pk_bf16_f32 v144, v80, v81
	v_cvt_pk_bf16_f32 v145, v82, v83
	v_cvt_pk_bf16_f32 v146, v84, v85
	v_cvt_pk_bf16_f32 v147, v86, v87
	v_cvt_pk_bf16_f32 v148, v88, v89
	v_cvt_pk_bf16_f32 v149, v90, v91
	v_cvt_pk_bf16_f32 v150, v92, v93
	v_cvt_pk_bf16_f32 v151, v94, v95
	v_permlane32_swap_b32_e32 v144, v146
	v_permlane32_swap_b32_e32 v145, v147
	v_permlane32_swap_b32_e32 v148, v150
	v_permlane32_swap_b32_e32 v149, v151
	v_cmp_gt_f32_e32 vcc, 1.0, v207
	s_cbranch_vccz .Lmla_noresc_o
	v_mul_f32_e32 v0, v207, v0
	v_mul_f32_e32 v1, v207, v1
	v_mul_f32_e32 v2, v207, v2
	v_mul_f32_e32 v3, v207, v3
	v_mul_f32_e32 v4, v207, v4
	v_mul_f32_e32 v5, v207, v5
	v_mul_f32_e32 v6, v207, v6
	v_mul_f32_e32 v7, v207, v7
	v_mul_f32_e32 v8, v207, v8
	v_mul_f32_e32 v9, v207, v9
	v_mul_f32_e32 v10, v207, v10
	v_mul_f32_e32 v11, v207, v11
	v_mul_f32_e32 v12, v207, v12
	v_mul_f32_e32 v13, v207, v13
	v_mul_f32_e32 v14, v207, v14
	v_mul_f32_e32 v15, v207, v15
	v_mul_f32_e32 v48, v207, v48
	v_mul_f32_e32 v49, v207, v49
	v_mul_f32_e32 v50, v207, v50
	v_mul_f32_e32 v51, v207, v51
	v_mul_f32_e32 v52, v207, v52
	v_mul_f32_e32 v53, v207, v53
	v_mul_f32_e32 v54, v207, v54
	v_mul_f32_e32 v55, v207, v55
	v_mul_f32_e32 v56, v207, v56
	v_mul_f32_e32 v57, v207, v57
	v_mul_f32_e32 v58, v207, v58
	v_mul_f32_e32 v59, v207, v59
	v_mul_f32_e32 v60, v207, v60
	v_mul_f32_e32 v61, v207, v61
	v_mul_f32_e32 v62, v207, v62
	v_mul_f32_e32 v63, v207, v63
	v_mul_f32_e32 v32, v207, v32
	v_mul_f32_e32 v33, v207, v33
	v_mul_f32_e32 v34, v207, v34
	v_mul_f32_e32 v35, v207, v35
	v_mul_f32_e32 v36, v207, v36
	v_mul_f32_e32 v37, v207, v37
	v_mul_f32_e32 v38, v207, v38
	v_mul_f32_e32 v39, v207, v39
	v_mul_f32_e32 v40, v207, v40
	v_mul_f32_e32 v41, v207, v41
	v_mul_f32_e32 v42, v207, v42
	v_mul_f32_e32 v43, v207, v43
	v_mul_f32_e32 v44, v207, v44
	v_mul_f32_e32 v45, v207, v45
	v_mul_f32_e32 v46, v207, v46
	v_mul_f32_e32 v47, v207, v47
	v_mul_f32_e32 v16, v207, v16
	v_mul_f32_e32 v17, v207, v17
	v_mul_f32_e32 v18, v207, v18
	v_mul_f32_e32 v19, v207, v19
	v_mul_f32_e32 v20, v207, v20
	v_mul_f32_e32 v21, v207, v21
	v_mul_f32_e32 v22, v207, v22
	v_mul_f32_e32 v23, v207, v23
	v_mul_f32_e32 v24, v207, v24
	v_mul_f32_e32 v25, v207, v25
	v_mul_f32_e32 v26, v207, v26
	v_mul_f32_e32 v27, v207, v27
	v_mul_f32_e32 v28, v207, v28
	v_mul_f32_e32 v29, v207, v29
	v_mul_f32_e32 v30, v207, v30
	v_mul_f32_e32 v31, v207, v31
.Lmla_noresc_o:
	s_add_i32 s58, s58, 1
	s_waitcnt vmcnt(0) lgkmcnt(0)
	s_barrier
	ds_read_b128 v[230:233], v193
	ds_read_b128 v[234:237], v186
	ds_read_b128 v[238:241], v187
	ds_read_b128 v[242:245], v188
	s_cmp_lt_u32 s58, s18
	s_cselect_b32 s0, 0, s18
	s_cselect_b32 s1, s6, s13
	s_lshl_b32 s0, s0, 6
	s_sub_i32 s0, s1, s0
	s_add_i32 s0, s51, s0
	s_add_i32 s0, s0, 64
	s_ashr_i32 s1, s0, 31
	s_lshl_b64 s[10:11], s[0:1], 12
	s_add_u32 s16, s20, s10
	s_addc_u32 s17, s21, s11
	v_exp_f32_e32 v64, v64
	v_exp_f32_e32 v65, v65
	v_add_f32_e32 v212, v64, v212
	v_exp_f32_e32 v66, v66
	v_add_f32_e32 v212, v65, v212
	v_exp_f32_e32 v67, v67
	s_waitcnt lgkmcnt(3)
	v_mfma_f32_32x32x16_bf16 v[80:95], v[230:233], v[124:127], 0
	ds_read_b128 v[230:233], v189
	s_mov_b32 m0, s22
	v_lshl_add_u64 v[254:255], v[164:165], 1, s[100:101]
	global_load_lds_dwordx4 v[254:255], off
	v_add_f32_e32 v212, v66, v212
	v_exp_f32_e32 v68, v68
	v_add_f32_e32 v212, v67, v212
	v_exp_f32_e32 v69, v69
	s_waitcnt lgkmcnt(3)
	v_mfma_f32_32x32x16_bf16 v[80:95], v[234:237], v[120:123], v[80:95]
	ds_read_b128 v[234:237], v190
	s_mov_b32 m0, s31
	v_lshl_add_u64 v[254:255], v[166:167], 1, s[100:101]
	global_load_lds_dwordx4 v[254:255], off
	v_add_f32_e32 v212, v68, v212
	v_exp_f32_e32 v70, v70
	v_add_f32_e32 v212, v69, v212
	v_exp_f32_e32 v71, v71
	s_waitcnt lgkmcnt(3)
	v_mfma_f32_32x32x16_bf16 v[80:95], v[238:241], v[116:119], v[80:95]
	ds_read_b128 v[238:241], v191
	v_add_f32_e32 v212, v70, v212
	v_exp_f32_e32 v72, v72
	v_add_f32_e32 v212, v71, v212
	v_exp_f32_e32 v73, v73
	s_waitcnt lgkmcnt(3)
	v_mfma_f32_32x32x16_bf16 v[80:95], v[242:245], v[112:115], v[80:95]
	ds_read_b128 v[242:245], v192
	s_mov_b32 m0, s44
	v_lshl_add_u64 v[254:255], v[160:161], 1, s[16:17]
	global_load_lds_dwordx4 v[254:255], off
	v_add_f32_e32 v212, v72, v212
	v_exp_f32_e32 v74, v74
	v_add_f32_e32 v212, v73, v212
	v_exp_f32_e32 v75, v75
	s_waitcnt lgkmcnt(3)
	v_mfma_f32_32x32x16_bf16 v[80:95], v[230:233], v[108:111], v[80:95]
	ds_read_b128 v[230:233], v203
	v_add_f32_e32 v212, v74, v212
	v_exp_f32_e32 v76, v76
	v_add_f32_e32 v212, v75, v212
	v_exp_f32_e32 v77, v77
	s_waitcnt lgkmcnt(3)
	v_mfma_f32_32x32x16_bf16 v[80:95], v[234:237], v[104:107], v[80:95]
	ds_read_b128 v[234:237], v204
	s_mov_b32 m0, s45
	v_lshl_add_u64 v[254:255], v[162:163], 1, s[16:17]
	global_load_lds_dwordx4 v[254:255], off
	v_add_f32_e32 v212, v76, v212
	v_exp_f32_e32 v78, v78
	v_add_f32_e32 v212, v77, v212
	v_exp_f32_e32 v79, v79
	s_waitcnt lgkmcnt(3)
	v_mfma_f32_32x32x16_bf16 v[80:95], v[238:241], v[100:103], v[80:95]
	ds_read_b128 v[238:241], v205
	v_add_f32_e32 v212, v78, v212
	v_add_f32_e32 v212, v79, v212
	v_mov_b32_e32 v213, v212
	s_waitcnt lgkmcnt(3)
	v_mfma_f32_32x32x16_bf16 v[80:95], v[242:245], v[96:99], v[80:95]
	ds_read_b128 v[242:245], v206
	s_mov_b32 m0, s49
	v_mad_i64_i32 v[254:255], s[0:1], s0, v180, v[168:169]
	global_load_lds_dwordx4 v[254:255], off
	s_add_u32 s100, s16, 0x100
	s_addc_u32 s101, s17, 0
	v_cvt_pk_bf16_f32 v152, v64, v65
	v_cvt_pk_bf16_f32 v153, v66, v67
	v_cvt_pk_bf16_f32 v154, v68, v69
	s_waitcnt lgkmcnt(3)
	v_mfma_f32_32x32x16_bf16 v[80:95], v[230:233], v[128:131], v[80:95]
	ds_read_b128 v[230:233], v193 offset:8192
	v_cvt_pk_bf16_f32 v155, v70, v71
	v_cvt_pk_bf16_f32 v156, v72, v73
	v_cvt_pk_bf16_f32 v157, v74, v75
	s_waitcnt lgkmcnt(3)
	v_mfma_f32_32x32x16_bf16 v[80:95], v[234:237], v[132:135], v[80:95]
	ds_read_b128 v[234:237], v186 offset:8192
	v_cvt_pk_bf16_f32 v158, v76, v77
	v_cvt_pk_bf16_f32 v159, v78, v79
	v_permlane32_swap_b32_e32 v212, v213
	s_waitcnt lgkmcnt(3)
	v_mfma_f32_32x32x16_bf16 v[80:95], v[238:241], v[136:139], v[80:95]
	ds_read_b128 v[238:241], v187 offset:8192
	v_add_f32_e32 v252, v212, v213
	v_fma_f32 v183, v207, v183, v252
	v_permlane32_swap_b32_e32 v152, v154
	s_waitcnt lgkmcnt(3)
	v_mfma_f32_32x32x16_bf16 v[80:95], v[242:245], v[140:143], v[80:95]
	ds_read_b128 v[242:245], v188 offset:8192
	v_permlane32_swap_b32_e32 v153, v155
	v_permlane32_swap_b32_e32 v156, v158
	v_permlane32_swap_b32_e32 v157, v159
	s_waitcnt lgkmcnt(3)
	v_mfma_f32_32x32x16_bf16 v[64:79], v[230:233], v[124:127], 0
	ds_read_b128 v[230:233], v189 offset:8192
	s_waitcnt lgkmcnt(3)
	v_mfma_f32_32x32x16_bf16 v[64:79], v[234:237], v[120:123], v[64:79]
	ds_read_b128 v[234:237], v190 offset:8192
	s_waitcnt lgkmcnt(3)
	v_mfma_f32_32x32x16_bf16 v[64:79], v[238:241], v[116:119], v[64:79]
	ds_read_b128 v[238:241], v191 offset:8192
	s_waitcnt lgkmcnt(3)
	v_mfma_f32_32x32x16_bf16 v[64:79], v[242:245], v[112:115], v[64:79]
	ds_read_b128 v[242:245], v192 offset:8192
	s_waitcnt lgkmcnt(3)
	v_mfma_f32_32x32x16_bf16 v[64:79], v[230:233], v[108:111], v[64:79]
	ds_read_b128 v[230:233], v203 offset:4096
	s_waitcnt lgkmcnt(3)
	v_mfma_f32_32x32x16_bf16 v[64:79], v[234:237], v[104:107], v[64:79]
	ds_read_b128 v[234:237], v204 offset:4096
	s_waitcnt lgkmcnt(3)
	v_mfma_f32_32x32x16_bf16 v[64:79], v[238:241], v[100:103], v[64:79]
	ds_read_b128 v[238:241], v205 offset:4096
	v_max_f32_e32 v249, v80, v81
	v_max3_f32 v249, v249, v82, v83
	s_waitcnt lgkmcnt(3)
	v_mfma_f32_32x32x16_bf16 v[64:79], v[242:245], v[96:99], v[64:79]
	ds_read_b128 v[242:245], v206 offset:4096
	v_max3_f32 v249, v249, v84, v85
	v_max3_f32 v249, v249, v86, v87
	s_waitcnt lgkmcnt(3)
	v_mfma_f32_32x32x16_bf16 v[64:79], v[230:233], v[128:131], v[64:79]
	ds_read_b64_tr_b16 v[214:215], v184
	ds_read_b64_tr_b16 v[216:217], v184 offset:2048
	v_max3_f32 v249, v249, v88, v89
	v_max3_f32 v249, v249, v90, v91
	s_waitcnt lgkmcnt(4)
	v_mfma_f32_32x32x16_bf16 v[64:79], v[234:237], v[132:135], v[64:79]
	ds_read_b64_tr_b16 v[218:219], v184 offset:4096
	ds_read_b64_tr_b16 v[220:221], v184 offset:6144
	v_max3_f32 v249, v249, v92, v93
	v_max3_f32 v249, v249, v94, v95
	s_waitcnt lgkmcnt(5)
	v_mfma_f32_32x32x16_bf16 v[64:79], v[238:241], v[136:139], v[64:79]
	ds_read_b64_tr_b16 v[222:223], v184 offset:8192
	ds_read_b64_tr_b16 v[224:225], v184 offset:10240
	s_waitcnt lgkmcnt(6)
	v_mfma_f32_32x32x16_bf16 v[64:79], v[242:245], v[140:143], v[64:79]
	ds_read_b64_tr_b16 v[226:227], v184 offset:12288
	ds_read_b64_tr_b16 v[228:229], v184 offset:14336
	s_waitcnt lgkmcnt(6)
	v_mfma_f32_32x32x16_bf16 v[0:15], v[214:217], v[144:147], v[0:15]
	ds_read_b64_tr_b16 v[214:215], v184 offset:512
	ds_read_b64_tr_b16 v[216:217], v184 offset:2560
	s_waitcnt lgkmcnt(6)
	v_mfma_f32_32x32x16_bf16 v[0:15], v[218:221], v[148:151], v[0:15]
	ds_read_b64_tr_b16 v[218:219], v184 offset:4608
	ds_read_b64_tr_b16 v[220:221], v184 offset:6656
	s_waitcnt lgkmcnt(6)
	v_mfma_f32_32x32x16_bf16 v[0:15], v[222:225], v[152:155], v[0:15]
	ds_read_b64_tr_b16 v[222:223], v184 offset:8704
	ds_read_b64_tr_b16 v[224:225], v184 offset:10752
	s_waitcnt lgkmcnt(6)
	v_mfma_f32_32x32x16_bf16 v[0:15], v[226:229], v[156:159], v[0:15]
	ds_read_b64_tr_b16 v[226:227], v184 offset:12800
	ds_read_b64_tr_b16 v[228:229], v184 offset:14848
	s_waitcnt lgkmcnt(6)
	v_mfma_f32_32x32x16_bf16 v[48:63], v[214:217], v[144:147], v[48:63]
	ds_read_b64_tr_b16 v[214:215], v184 offset:1024
	ds_read_b64_tr_b16 v[216:217], v184 offset:3072
	v_max3_f32 v249, v249, v64, v65
	v_max3_f32 v249, v249, v66, v67
	v_max3_f32 v249, v249, v68, v69
	v_max3_f32 v249, v249, v70, v71
	v_max3_f32 v249, v249, v72, v73
	v_max3_f32 v249, v249, v74, v75
	v_max3_f32 v249, v249, v76, v77
	v_max3_f32 v249, v249, v78, v79
	s_waitcnt lgkmcnt(6)
	v_mfma_f32_32x32x16_bf16 v[48:63], v[218:221], v[148:151], v[48:63]
	ds_read_b64_tr_b16 v[218:219], v184 offset:5120
	ds_read_b64_tr_b16 v[220:221], v184 offset:7168
	v_mov_b32_e32 v250, v249
	s_nop 1
	v_permlane32_swap_b32_e32 v249, v250
	v_max_f32_e32 v249, v249, v250
	v_sub_f32_e32 v250, v249, v208
	v_cmp_ge_f32_e32 vcc, s40, v250
	v_max_f32_e32 v249, v208, v249
	v_sub_f32_e32 v250, v208, v249
	s_waitcnt lgkmcnt(6)
	v_mfma_f32_32x32x16_bf16 v[48:63], v[222:225], v[152:155], v[48:63]
	ds_read_b64_tr_b16 v[222:223], v184 offset:9216
	ds_read_b64_tr_b16 v[224:225], v184 offset:11264
	v_mul_f32_e32 v250, 0x3dd53b94, v250
	v_exp_f32_e32 v250, v250
	s_cmp_eq_u64 vcc, exec
	s_cselect_b64 s[10:11], -1, 0
	v_cndmask_b32_e64 v207, v250, 1.0, s[10:11]
	v_cndmask_b32_e64 v208, v249, v208, s[10:11]
	v_mul_f32_e32 v251, 0xbdd53b94, v208
	v_fmamk_f32 v80, v80, 0x3dd53b94, v251
	s_waitcnt lgkmcnt(6)
	v_mfma_f32_32x32x16_bf16 v[48:63], v[226:229], v[156:159], v[48:63]
	ds_read_b64_tr_b16 v[226:227], v184 offset:13312
	ds_read_b64_tr_b16 v[228:229], v184 offset:15360
	v_fmamk_f32 v81, v81, 0x3dd53b94, v251
	v_fmamk_f32 v82, v82, 0x3dd53b94, v251
	v_fmamk_f32 v83, v83, 0x3dd53b94, v251
	v_fmamk_f32 v84, v84, 0x3dd53b94, v251
	v_fmamk_f32 v85, v85, 0x3dd53b94, v251
	v_fmamk_f32 v86, v86, 0x3dd53b94, v251
	v_fmamk_f32 v87, v87, 0x3dd53b94, v251
	s_waitcnt lgkmcnt(6)
	v_mfma_f32_32x32x16_bf16 v[32:47], v[214:217], v[144:147], v[32:47]
	ds_read_b64_tr_b16 v[214:215], v184 offset:1536
	ds_read_b64_tr_b16 v[216:217], v184 offset:3584
	v_fmamk_f32 v88, v88, 0x3dd53b94, v251
	v_fmamk_f32 v89, v89, 0x3dd53b94, v251
	v_fmamk_f32 v90, v90, 0x3dd53b94, v251
	v_fmamk_f32 v91, v91, 0x3dd53b94, v251
	v_fmamk_f32 v92, v92, 0x3dd53b94, v251
	v_fmamk_f32 v93, v93, 0x3dd53b94, v251
	v_fmamk_f32 v94, v94, 0x3dd53b94, v251
	s_waitcnt lgkmcnt(6)
	v_mfma_f32_32x32x16_bf16 v[32:47], v[218:221], v[148:151], v[32:47]
	ds_read_b64_tr_b16 v[218:219], v184 offset:5632
	ds_read_b64_tr_b16 v[220:221], v184 offset:7680
	v_fmamk_f32 v95, v95, 0x3dd53b94, v251
	v_exp_f32_e32 v80, v80
	v_fmamk_f32 v64, v64, 0x3dd53b94, v251
	v_exp_f32_e32 v81, v81
	v_fmamk_f32 v65, v65, 0x3dd53b94, v251
	v_add_f32_e32 v212, 0, v80
	v_exp_f32_e32 v82, v82
	s_waitcnt lgkmcnt(6)
	v_mfma_f32_32x32x16_bf16 v[32:47], v[222:225], v[152:155], v[32:47]
	ds_read_b64_tr_b16 v[222:223], v184 offset:9728
	ds_read_b64_tr_b16 v[224:225], v184 offset:11776
	v_fmamk_f32 v66, v66, 0x3dd53b94, v251
	v_add_f32_e32 v212, v81, v212
	v_exp_f32_e32 v83, v83
	v_fmamk_f32 v67, v67, 0x3dd53b94, v251
	v_add_f32_e32 v212, v82, v212
	v_exp_f32_e32 v84, v84
	v_fmamk_f32 v68, v68, 0x3dd53b94, v251
	s_waitcnt lgkmcnt(6)
	v_mfma_f32_32x32x16_bf16 v[32:47], v[226:229], v[156:159], v[32:47]
	ds_read_b64_tr_b16 v[226:227], v184 offset:13824
	ds_read_b64_tr_b16 v[228:229], v184 offset:15872
	v_add_f32_e32 v212, v83, v212
	v_exp_f32_e32 v85, v85
	v_fmamk_f32 v69, v69, 0x3dd53b94, v251
	v_add_f32_e32 v212, v84, v212
	v_exp_f32_e32 v86, v86
	v_fmamk_f32 v70, v70, 0x3dd53b94, v251
	v_add_f32_e32 v212, v85, v212
	s_waitcnt lgkmcnt(6)
	v_mfma_f32_32x32x16_bf16 v[16:31], v[214:217], v[144:147], v[16:31]
	v_exp_f32_e32 v87, v87
	v_fmamk_f32 v71, v71, 0x3dd53b94, v251
	v_add_f32_e32 v212, v86, v212
	v_exp_f32_e32 v88, v88
	v_fmamk_f32 v72, v72, 0x3dd53b94, v251
	v_add_f32_e32 v212, v87, v212
	v_exp_f32_e32 v89, v89
	s_waitcnt lgkmcnt(4)
	v_mfma_f32_32x32x16_bf16 v[16:31], v[218:221], v[148:151], v[16:31]
	v_fmamk_f32 v73, v73, 0x3dd53b94, v251
	v_add_f32_e32 v212, v88, v212
	v_exp_f32_e32 v90, v90
	v_fmamk_f32 v74, v74, 0x3dd53b94, v251
	v_add_f32_e32 v212, v89, v212
	v_exp_f32_e32 v91, v91
	v_fmamk_f32 v75, v75, 0x3dd53b94, v251
	s_waitcnt lgkmcnt(2)
	v_mfma_f32_32x32x16_bf16 v[16:31], v[222:225], v[152:155], v[16:31]
	v_add_f32_e32 v212, v90, v212
	v_exp_f32_e32 v92, v92
	v_fmamk_f32 v76, v76, 0x3dd53b94, v251
	v_add_f32_e32 v212, v91, v212
	v_exp_f32_e32 v93, v93
	v_fmamk_f32 v77, v77, 0x3dd53b94, v251
	v_add_f32_e32 v212, v92, v212
	s_waitcnt lgkmcnt(0)
	v_mfma_f32_32x32x16_bf16 v[16:31], v[226:229], v[156:159], v[16:31]
	v_exp_f32_e32 v94, v94
	v_fmamk_f32 v78, v78, 0x3dd53b94, v251
	v_add_f32_e32 v212, v93, v212
	v_exp_f32_e32 v95, v95
	v_fmamk_f32 v79, v79, 0x3dd53b94, v251
	v_add_f32_e32 v212, v94, v212
	v_add_f32_e32 v212, v95, v212
	v_cvt_pk_bf16_f32 v144, v80, v81
	v_cvt_pk_bf16_f32 v145, v82, v83
	v_cvt_pk_bf16_f32 v146, v84, v85
	v_cvt_pk_bf16_f32 v147, v86, v87
	v_cvt_pk_bf16_f32 v148, v88, v89
	v_cvt_pk_bf16_f32 v149, v90, v91
	v_cvt_pk_bf16_f32 v150, v92, v93
	v_cvt_pk_bf16_f32 v151, v94, v95
	v_permlane32_swap_b32_e32 v144, v146
	v_permlane32_swap_b32_e32 v145, v147
	v_permlane32_swap_b32_e32 v148, v150
	v_permlane32_swap_b32_e32 v149, v151
	v_cmp_gt_f32_e32 vcc, 1.0, v207
	s_cbranch_vccz .Lmla_noresc_e
	v_mul_f32_e32 v0, v207, v0
	v_mul_f32_e32 v1, v207, v1
	v_mul_f32_e32 v2, v207, v2
	v_mul_f32_e32 v3, v207, v3
	v_mul_f32_e32 v4, v207, v4
	v_mul_f32_e32 v5, v207, v5
	v_mul_f32_e32 v6, v207, v6
	v_mul_f32_e32 v7, v207, v7
	v_mul_f32_e32 v8, v207, v8
	v_mul_f32_e32 v9, v207, v9
	v_mul_f32_e32 v10, v207, v10
	v_mul_f32_e32 v11, v207, v11
	v_mul_f32_e32 v12, v207, v12
	v_mul_f32_e32 v13, v207, v13
	v_mul_f32_e32 v14, v207, v14
	v_mul_f32_e32 v15, v207, v15
	v_mul_f32_e32 v48, v207, v48
	v_mul_f32_e32 v49, v207, v49
	v_mul_f32_e32 v50, v207, v50
	v_mul_f32_e32 v51, v207, v51
	v_mul_f32_e32 v52, v207, v52
	v_mul_f32_e32 v53, v207, v53
	v_mul_f32_e32 v54, v207, v54
	v_mul_f32_e32 v55, v207, v55
	v_mul_f32_e32 v56, v207, v56
	v_mul_f32_e32 v57, v207, v57
	v_mul_f32_e32 v58, v207, v58
	v_mul_f32_e32 v59, v207, v59
	v_mul_f32_e32 v60, v207, v60
	v_mul_f32_e32 v61, v207, v61
	v_mul_f32_e32 v62, v207, v62
	v_mul_f32_e32 v63, v207, v63
	v_mul_f32_e32 v32, v207, v32
	v_mul_f32_e32 v33, v207, v33
	v_mul_f32_e32 v34, v207, v34
	v_mul_f32_e32 v35, v207, v35
	v_mul_f32_e32 v36, v207, v36
	v_mul_f32_e32 v37, v207, v37
	v_mul_f32_e32 v38, v207, v38
	v_mul_f32_e32 v39, v207, v39
	v_mul_f32_e32 v40, v207, v40
	v_mul_f32_e32 v41, v207, v41
	v_mul_f32_e32 v42, v207, v42
	v_mul_f32_e32 v43, v207, v43
	v_mul_f32_e32 v44, v207, v44
	v_mul_f32_e32 v45, v207, v45
	v_mul_f32_e32 v46, v207, v46
	v_mul_f32_e32 v47, v207, v47
	v_mul_f32_e32 v16, v207, v16
	v_mul_f32_e32 v17, v207, v17
	v_mul_f32_e32 v18, v207, v18
	v_mul_f32_e32 v19, v207, v19
	v_mul_f32_e32 v20, v207, v20
	v_mul_f32_e32 v21, v207, v21
	v_mul_f32_e32 v22, v207, v22
	v_mul_f32_e32 v23, v207, v23
	v_mul_f32_e32 v24, v207, v24
	v_mul_f32_e32 v25, v207, v25
	v_mul_f32_e32 v26, v207, v26
	v_mul_f32_e32 v27, v207, v27
	v_mul_f32_e32 v28, v207, v28
	v_mul_f32_e32 v29, v207, v29
	v_mul_f32_e32 v30, v207, v30
	v_mul_f32_e32 v31, v207, v31
.Lmla_noresc_e:
	s_add_i32 s58, s58, 1
	s_addk_i32 s51, 0x80
	s_waitcnt vmcnt(0) lgkmcnt(0)
	s_barrier
	s_cmp_ge_u32 s58, s19
	s_cbranch_scc0 .Lmla_loop
	ds_read_b128 v[230:233], v193 offset:24576
	ds_read_b128 v[234:237], v186 offset:24576
	ds_read_b128 v[238:241], v187 offset:24576
	ds_read_b128 v[242:245], v188 offset:24576
	v_exp_f32_e32 v64, v64
	v_exp_f32_e32 v65, v65
	v_add_f32_e32 v212, v64, v212
	v_exp_f32_e32 v66, v66
	v_add_f32_e32 v212, v65, v212
	v_exp_f32_e32 v67, v67
	s_waitcnt lgkmcnt(3)
	v_mfma_f32_32x32x16_bf16 v[80:95], v[230:233], v[124:127], 0
	ds_read_b128 v[230:233], v189 offset:24576
	s_mov_b32 m0, s54
	v_lshl_add_u64 v[254:255], v[164:165], 1, s[100:101]
	global_load_lds_dwordx4 v[254:255], off
	v_add_f32_e32 v212, v66, v212
	v_exp_f32_e32 v68, v68
	v_add_f32_e32 v212, v67, v212
	v_exp_f32_e32 v69, v69
	s_waitcnt lgkmcnt(3)
	v_mfma_f32_32x32x16_bf16 v[80:95], v[234:237], v[120:123], v[80:95]
	ds_read_b128 v[234:237], v190 offset:24576
	s_mov_b32 m0, s55
	v_lshl_add_u64 v[254:255], v[166:167], 1, s[100:101]
	global_load_lds_dwordx4 v[254:255], off
	v_add_f32_e32 v212, v68, v212
	v_exp_f32_e32 v70, v70
	v_add_f32_e32 v212, v69, v212
	v_exp_f32_e32 v71, v71
	s_waitcnt lgkmcnt(3)
	v_mfma_f32_32x32x16_bf16 v[80:95], v[238:241], v[116:119], v[80:95]
	ds_read_b128 v[238:241], v191 offset:24576
	v_add_f32_e32 v212, v70, v212
	v_exp_f32_e32 v72, v72
	v_add_f32_e32 v212, v71, v212
	v_exp_f32_e32 v73, v73
	s_waitcnt lgkmcnt(3)
	v_mfma_f32_32x32x16_bf16 v[80:95], v[242:245], v[112:115], v[80:95]
	ds_read_b128 v[242:245], v192 offset:24576
	v_add_f32_e32 v212, v72, v212
	v_exp_f32_e32 v74, v74
	v_add_f32_e32 v212, v73, v212
	v_exp_f32_e32 v75, v75
	s_waitcnt lgkmcnt(3)
	v_mfma_f32_32x32x16_bf16 v[80:95], v[230:233], v[108:111], v[80:95]
	ds_read_b128 v[230:233], v203 offset:24576
	v_add_f32_e32 v212, v74, v212
	v_exp_f32_e32 v76, v76
	v_add_f32_e32 v212, v75, v212
	v_exp_f32_e32 v77, v77
	s_waitcnt lgkmcnt(3)
	v_mfma_f32_32x32x16_bf16 v[80:95], v[234:237], v[104:107], v[80:95]
	ds_read_b128 v[234:237], v204 offset:24576
	v_add_f32_e32 v212, v76, v212
	v_exp_f32_e32 v78, v78
	v_add_f32_e32 v212, v77, v212
	v_exp_f32_e32 v79, v79
	s_waitcnt lgkmcnt(3)
	v_mfma_f32_32x32x16_bf16 v[80:95], v[238:241], v[100:103], v[80:95]
	ds_read_b128 v[238:241], v205 offset:24576
	v_add_f32_e32 v212, v78, v212
	v_add_f32_e32 v212, v79, v212
	v_mov_b32_e32 v213, v212
	s_waitcnt lgkmcnt(3)
	v_mfma_f32_32x32x16_bf16 v[80:95], v[242:245], v[96:99], v[80:95]
	ds_read_b128 v[242:245], v206 offset:24576
	v_cvt_pk_bf16_f32 v152, v64, v65
	v_cvt_pk_bf16_f32 v153, v66, v67
	v_cvt_pk_bf16_f32 v154, v68, v69
	s_waitcnt lgkmcnt(3)
	v_mfma_f32_32x32x16_bf16 v[80:95], v[230:233], v[128:131], v[80:95]
	ds_read_b128 v[230:233], v193 offset:32768
	v_cvt_pk_bf16_f32 v155, v70, v71
	v_cvt_pk_bf16_f32 v156, v72, v73
	v_cvt_pk_bf16_f32 v157, v74, v75
	s_waitcnt lgkmcnt(3)
	v_mfma_f32_32x32x16_bf16 v[80:95], v[234:237], v[132:135], v[80:95]
	ds_read_b128 v[234:237], v186 offset:32768
	v_cvt_pk_bf16_f32 v158, v76, v77
	v_cvt_pk_bf16_f32 v159, v78, v79
	v_permlane32_swap_b32_e32 v212, v213
	s_waitcnt lgkmcnt(3)
	v_mfma_f32_32x32x16_bf16 v[80:95], v[238:241], v[136:139], v[80:95]
	ds_read_b128 v[238:241], v187 offset:32768
	v_add_f32_e32 v252, v212, v213
	v_fma_f32 v183, v207, v183, v252
	v_permlane32_swap_b32_e32 v152, v154
	s_waitcnt lgkmcnt(3)
	v_mfma_f32_32x32x16_bf16 v[80:95], v[242:245], v[140:143], v[80:95]
	ds_read_b128 v[242:245], v188 offset:32768
	v_permlane32_swap_b32_e32 v153, v155
	v_permlane32_swap_b32_e32 v156, v158
	v_permlane32_swap_b32_e32 v157, v159
	s_waitcnt lgkmcnt(3)
	v_mfma_f32_32x32x16_bf16 v[64:79], v[230:233], v[124:127], 0
	ds_read_b128 v[230:233], v189 offset:32768
	s_waitcnt lgkmcnt(3)
	v_mfma_f32_32x32x16_bf16 v[64:79], v[234:237], v[120:123], v[64:79]
	ds_read_b128 v[234:237], v190 offset:32768
	s_waitcnt lgkmcnt(3)
	v_mfma_f32_32x32x16_bf16 v[64:79], v[238:241], v[116:119], v[64:79]
	ds_read_b128 v[238:241], v191 offset:32768
	s_waitcnt lgkmcnt(3)
	v_mfma_f32_32x32x16_bf16 v[64:79], v[242:245], v[112:115], v[64:79]
	ds_read_b128 v[242:245], v192 offset:32768
	s_waitcnt lgkmcnt(3)
	v_mfma_f32_32x32x16_bf16 v[64:79], v[230:233], v[108:111], v[64:79]
	ds_read_b128 v[230:233], v203 offset:28672
	s_waitcnt lgkmcnt(3)
	v_mfma_f32_32x32x16_bf16 v[64:79], v[234:237], v[104:107], v[64:79]
	ds_read_b128 v[234:237], v204 offset:28672
	s_waitcnt lgkmcnt(3)
	v_mfma_f32_32x32x16_bf16 v[64:79], v[238:241], v[100:103], v[64:79]
	ds_read_b128 v[238:241], v205 offset:28672
	v_max_f32_e32 v249, v80, v81
	v_max3_f32 v249, v249, v82, v83
	s_waitcnt lgkmcnt(3)
	v_mfma_f32_32x32x16_bf16 v[64:79], v[242:245], v[96:99], v[64:79]
	ds_read_b128 v[242:245], v206 offset:28672
	v_max3_f32 v249, v249, v84, v85
	v_max3_f32 v249, v249, v86, v87
	s_waitcnt lgkmcnt(3)
	v_mfma_f32_32x32x16_bf16 v[64:79], v[230:233], v[128:131], v[64:79]
	ds_read_b64_tr_b16 v[214:215], v185
	ds_read_b64_tr_b16 v[216:217], v185 offset:2048
	v_max3_f32 v249, v249, v88, v89
	v_max3_f32 v249, v249, v90, v91
	s_waitcnt lgkmcnt(4)
	v_mfma_f32_32x32x16_bf16 v[64:79], v[234:237], v[132:135], v[64:79]
	ds_read_b64_tr_b16 v[218:219], v185 offset:4096
	ds_read_b64_tr_b16 v[220:221], v185 offset:6144
	v_max3_f32 v249, v249, v92, v93
	v_max3_f32 v249, v249, v94, v95
	s_waitcnt lgkmcnt(5)
	v_mfma_f32_32x32x16_bf16 v[64:79], v[238:241], v[136:139], v[64:79]
	ds_read_b64_tr_b16 v[222:223], v185 offset:8192
	ds_read_b64_tr_b16 v[224:225], v185 offset:10240
	s_waitcnt lgkmcnt(6)
	v_mfma_f32_32x32x16_bf16 v[64:79], v[242:245], v[140:143], v[64:79]
	ds_read_b64_tr_b16 v[226:227], v185 offset:12288
	ds_read_b64_tr_b16 v[228:229], v185 offset:14336
	s_waitcnt lgkmcnt(6)
	v_mfma_f32_32x32x16_bf16 v[0:15], v[214:217], v[144:147], v[0:15]
	ds_read_b64_tr_b16 v[214:215], v185 offset:512
	ds_read_b64_tr_b16 v[216:217], v185 offset:2560
	s_waitcnt lgkmcnt(6)
	v_mfma_f32_32x32x16_bf16 v[0:15], v[218:221], v[148:151], v[0:15]
	ds_read_b64_tr_b16 v[218:219], v185 offset:4608
	ds_read_b64_tr_b16 v[220:221], v185 offset:6656
	s_waitcnt lgkmcnt(6)
	v_mfma_f32_32x32x16_bf16 v[0:15], v[222:225], v[152:155], v[0:15]
	ds_read_b64_tr_b16 v[222:223], v185 offset:8704
	ds_read_b64_tr_b16 v[224:225], v185 offset:10752
	s_waitcnt lgkmcnt(6)
	v_mfma_f32_32x32x16_bf16 v[0:15], v[226:229], v[156:159], v[0:15]
	ds_read_b64_tr_b16 v[226:227], v185 offset:12800
	ds_read_b64_tr_b16 v[228:229], v185 offset:14848
	s_waitcnt lgkmcnt(6)
	v_mfma_f32_32x32x16_bf16 v[48:63], v[214:217], v[144:147], v[48:63]
	ds_read_b64_tr_b16 v[214:215], v185 offset:1024
	ds_read_b64_tr_b16 v[216:217], v185 offset:3072
	v_max3_f32 v249, v249, v64, v65
	v_max3_f32 v249, v249, v66, v67
	v_max3_f32 v249, v249, v68, v69
	v_max3_f32 v249, v249, v70, v71
	v_max3_f32 v249, v249, v72, v73
	v_max3_f32 v249, v249, v74, v75
	v_max3_f32 v249, v249, v76, v77
	v_max3_f32 v249, v249, v78, v79
	s_waitcnt lgkmcnt(6)
	v_mfma_f32_32x32x16_bf16 v[48:63], v[218:221], v[148:151], v[48:63]
	ds_read_b64_tr_b16 v[218:219], v185 offset:5120
	ds_read_b64_tr_b16 v[220:221], v185 offset:7168
	v_mov_b32_e32 v250, v249
	s_nop 1
	v_permlane32_swap_b32_e32 v249, v250
	v_max_f32_e32 v249, v249, v250
	v_sub_f32_e32 v250, v249, v208
	v_cmp_ge_f32_e32 vcc, s40, v250
	v_max_f32_e32 v249, v208, v249
	v_sub_f32_e32 v250, v208, v249
	s_waitcnt lgkmcnt(6)
	v_mfma_f32_32x32x16_bf16 v[48:63], v[222:225], v[152:155], v[48:63]
	ds_read_b64_tr_b16 v[222:223], v185 offset:9216
	ds_read_b64_tr_b16 v[224:225], v185 offset:11264
	v_mul_f32_e32 v250, 0x3dd53b94, v250
	v_exp_f32_e32 v250, v250
	s_cmp_eq_u64 vcc, exec
	s_cselect_b64 s[10:11], -1, 0
	v_cndmask_b32_e64 v207, v250, 1.0, s[10:11]
	v_cndmask_b32_e64 v208, v249, v208, s[10:11]
	v_mul_f32_e32 v251, 0xbdd53b94, v208
	v_fmamk_f32 v80, v80, 0x3dd53b94, v251
	s_waitcnt lgkmcnt(6)
	v_mfma_f32_32x32x16_bf16 v[48:63], v[226:229], v[156:159], v[48:63]
	ds_read_b64_tr_b16 v[226:227], v185 offset:13312
	ds_read_b64_tr_b16 v[228:229], v185 offset:15360
	v_fmamk_f32 v81, v81, 0x3dd53b94, v251
	v_fmamk_f32 v82, v82, 0x3dd53b94, v251
	v_fmamk_f32 v83, v83, 0x3dd53b94, v251
	v_fmamk_f32 v84, v84, 0x3dd53b94, v251
	v_fmamk_f32 v85, v85, 0x3dd53b94, v251
	v_fmamk_f32 v86, v86, 0x3dd53b94, v251
	v_fmamk_f32 v87, v87, 0x3dd53b94, v251
	s_waitcnt lgkmcnt(6)
	v_mfma_f32_32x32x16_bf16 v[32:47], v[214:217], v[144:147], v[32:47]
	ds_read_b64_tr_b16 v[214:215], v185 offset:1536
	ds_read_b64_tr_b16 v[216:217], v185 offset:3584
	v_fmamk_f32 v88, v88, 0x3dd53b94, v251
	v_fmamk_f32 v89, v89, 0x3dd53b94, v251
	v_fmamk_f32 v90, v90, 0x3dd53b94, v251
	v_fmamk_f32 v91, v91, 0x3dd53b94, v251
	v_fmamk_f32 v92, v92, 0x3dd53b94, v251
	v_fmamk_f32 v93, v93, 0x3dd53b94, v251
	v_fmamk_f32 v94, v94, 0x3dd53b94, v251
	s_waitcnt lgkmcnt(6)
	v_mfma_f32_32x32x16_bf16 v[32:47], v[218:221], v[148:151], v[32:47]
	ds_read_b64_tr_b16 v[218:219], v185 offset:5632
	ds_read_b64_tr_b16 v[220:221], v185 offset:7680
	v_fmamk_f32 v95, v95, 0x3dd53b94, v251
	v_exp_f32_e32 v80, v80
	v_fmamk_f32 v64, v64, 0x3dd53b94, v251
	v_exp_f32_e32 v81, v81
	v_fmamk_f32 v65, v65, 0x3dd53b94, v251
	v_add_f32_e32 v212, 0, v80
	v_exp_f32_e32 v82, v82
	s_waitcnt lgkmcnt(6)
	v_mfma_f32_32x32x16_bf16 v[32:47], v[222:225], v[152:155], v[32:47]
	ds_read_b64_tr_b16 v[222:223], v185 offset:9728
	ds_read_b64_tr_b16 v[224:225], v185 offset:11776
	v_fmamk_f32 v66, v66, 0x3dd53b94, v251
	v_add_f32_e32 v212, v81, v212
	v_exp_f32_e32 v83, v83
	v_fmamk_f32 v67, v67, 0x3dd53b94, v251
	v_add_f32_e32 v212, v82, v212
	v_exp_f32_e32 v84, v84
	v_fmamk_f32 v68, v68, 0x3dd53b94, v251
	s_waitcnt lgkmcnt(6)
	v_mfma_f32_32x32x16_bf16 v[32:47], v[226:229], v[156:159], v[32:47]
	ds_read_b64_tr_b16 v[226:227], v185 offset:13824
	ds_read_b64_tr_b16 v[228:229], v185 offset:15872
	v_add_f32_e32 v212, v83, v212
	v_exp_f32_e32 v85, v85
	v_fmamk_f32 v69, v69, 0x3dd53b94, v251
	v_add_f32_e32 v212, v84, v212
	v_exp_f32_e32 v86, v86
	v_fmamk_f32 v70, v70, 0x3dd53b94, v251
	v_add_f32_e32 v212, v85, v212
	s_waitcnt lgkmcnt(6)
	v_mfma_f32_32x32x16_bf16 v[16:31], v[214:217], v[144:147], v[16:31]
	v_exp_f32_e32 v87, v87
	v_fmamk_f32 v71, v71, 0x3dd53b94, v251
	v_add_f32_e32 v212, v86, v212
	v_exp_f32_e32 v88, v88
	v_fmamk_f32 v72, v72, 0x3dd53b94, v251
	v_add_f32_e32 v212, v87, v212
	v_exp_f32_e32 v89, v89
	s_waitcnt lgkmcnt(4)
	v_mfma_f32_32x32x16_bf16 v[16:31], v[218:221], v[148:151], v[16:31]
	v_fmamk_f32 v73, v73, 0x3dd53b94, v251
	v_add_f32_e32 v212, v88, v212
	v_exp_f32_e32 v90, v90
	v_fmamk_f32 v74, v74, 0x3dd53b94, v251
	v_add_f32_e32 v212, v89, v212
	v_exp_f32_e32 v91, v91
	v_fmamk_f32 v75, v75, 0x3dd53b94, v251
	s_waitcnt lgkmcnt(2)
	v_mfma_f32_32x32x16_bf16 v[16:31], v[222:225], v[152:155], v[16:31]
	v_add_f32_e32 v212, v90, v212
	v_exp_f32_e32 v92, v92
	v_fmamk_f32 v76, v76, 0x3dd53b94, v251
	v_add_f32_e32 v212, v91, v212
	v_exp_f32_e32 v93, v93
	v_fmamk_f32 v77, v77, 0x3dd53b94, v251
	v_add_f32_e32 v212, v92, v212
	s_waitcnt lgkmcnt(0)
	v_mfma_f32_32x32x16_bf16 v[16:31], v[226:229], v[156:159], v[16:31]
	v_exp_f32_e32 v94, v94
	v_fmamk_f32 v78, v78, 0x3dd53b94, v251
	v_add_f32_e32 v212, v93, v212
	v_exp_f32_e32 v95, v95
	v_fmamk_f32 v79, v79, 0x3dd53b94, v251
	v_add_f32_e32 v212, v94, v212
	v_add_f32_e32 v212, v95, v212
	v_cvt_pk_bf16_f32 v144, v80, v81
	v_cvt_pk_bf16_f32 v145, v82, v83
	v_cvt_pk_bf16_f32 v146, v84, v85
	v_cvt_pk_bf16_f32 v147, v86, v87
	v_cvt_pk_bf16_f32 v148, v88, v89
	v_cvt_pk_bf16_f32 v149, v90, v91
	v_cvt_pk_bf16_f32 v150, v92, v93
	v_cvt_pk_bf16_f32 v151, v94, v95
	v_permlane32_swap_b32_e32 v144, v146
	v_permlane32_swap_b32_e32 v145, v147
	v_permlane32_swap_b32_e32 v148, v150
	v_permlane32_swap_b32_e32 v149, v151
	v_cmp_gt_f32_e32 vcc, 1.0, v207
	s_cbranch_vccz .Lmla_noresc_t
	v_mul_f32_e32 v0, v207, v0
	v_mul_f32_e32 v1, v207, v1
	v_mul_f32_e32 v2, v207, v2
	v_mul_f32_e32 v3, v207, v3
	v_mul_f32_e32 v4, v207, v4
	v_mul_f32_e32 v5, v207, v5
	v_mul_f32_e32 v6, v207, v6
	v_mul_f32_e32 v7, v207, v7
	v_mul_f32_e32 v8, v207, v8
	v_mul_f32_e32 v9, v207, v9
	v_mul_f32_e32 v10, v207, v10
	v_mul_f32_e32 v11, v207, v11
	v_mul_f32_e32 v12, v207, v12
	v_mul_f32_e32 v13, v207, v13
	v_mul_f32_e32 v14, v207, v14
	v_mul_f32_e32 v15, v207, v15
	v_mul_f32_e32 v48, v207, v48
	v_mul_f32_e32 v49, v207, v49
	v_mul_f32_e32 v50, v207, v50
	v_mul_f32_e32 v51, v207, v51
	v_mul_f32_e32 v52, v207, v52
	v_mul_f32_e32 v53, v207, v53
	v_mul_f32_e32 v54, v207, v54
	v_mul_f32_e32 v55, v207, v55
	v_mul_f32_e32 v56, v207, v56
	v_mul_f32_e32 v57, v207, v57
	v_mul_f32_e32 v58, v207, v58
	v_mul_f32_e32 v59, v207, v59
	v_mul_f32_e32 v60, v207, v60
	v_mul_f32_e32 v61, v207, v61
	v_mul_f32_e32 v62, v207, v62
	v_mul_f32_e32 v63, v207, v63
	v_mul_f32_e32 v32, v207, v32
	v_mul_f32_e32 v33, v207, v33
	v_mul_f32_e32 v34, v207, v34
	v_mul_f32_e32 v35, v207, v35
	v_mul_f32_e32 v36, v207, v36
	v_mul_f32_e32 v37, v207, v37
	v_mul_f32_e32 v38, v207, v38
	v_mul_f32_e32 v39, v207, v39
	v_mul_f32_e32 v40, v207, v40
	v_mul_f32_e32 v41, v207, v41
	v_mul_f32_e32 v42, v207, v42
	v_mul_f32_e32 v43, v207, v43
	v_mul_f32_e32 v44, v207, v44
	v_mul_f32_e32 v45, v207, v45
	v_mul_f32_e32 v46, v207, v46
	v_mul_f32_e32 v47, v207, v47
	v_mul_f32_e32 v16, v207, v16
	v_mul_f32_e32 v17, v207, v17
	v_mul_f32_e32 v18, v207, v18
	v_mul_f32_e32 v19, v207, v19
	v_mul_f32_e32 v20, v207, v20
	v_mul_f32_e32 v21, v207, v21
	v_mul_f32_e32 v22, v207, v22
	v_mul_f32_e32 v23, v207, v23
	v_mul_f32_e32 v24, v207, v24
	v_mul_f32_e32 v25, v207, v25
	v_mul_f32_e32 v26, v207, v26
	v_mul_f32_e32 v27, v207, v27
	v_mul_f32_e32 v28, v207, v28
	v_mul_f32_e32 v29, v207, v29
	v_mul_f32_e32 v30, v207, v30
	v_mul_f32_e32 v31, v207, v31
